# stack: + selected-branch off-lane exp masking via +1e30 max operand, GU first-iteration waits do not drain epilogue stores
# speedup vs baseline: 1.0029x; 1.0029x over previous
_Z4mega4Args:
	s_mov_b32 s100, 0
	s_load_dwordx8 s[12:19], s[0:1], 0xc0
	s_mov_b32 s89, s2
	s_add_u32 s2, s0, 0xd8
	s_addc_u32 s3, s1, 0
	v_and_b32_e32 v169, 0x3ff, v0
	v_writelane_b32 v252, s2, 0
	v_cmp_gt_u32_e32 vcc, 2, v169
	s_nop 0
	v_writelane_b32 v252, s3, 1
	s_and_saveexec_b64 s[2:3], vcc
	v_lshl_add_u32 v1, v169, 2, 0
	v_add_u32_e32 v1, 0x23fc0, v1
	v_mov_b32_e32 v2, 0
	ds_write_b32 v1, v2
	s_or_b64 exec, exec, s[2:3]
	s_waitcnt lgkmcnt(0)
	s_barrier
	s_getreg_b32 s2, hwreg(HW_REG_XCC_ID, 0, 4)
	s_and_b32 s6, s2, 15
	v_cmp_eq_u32_e64 s[4:5], 0, v169
	s_mov_b64 s[2:3], exec
	s_nop 0
	v_writelane_b32 v252, s4, 2
	s_nop 1
	v_writelane_b32 v252, s5, 3
	s_and_b64 s[4:5], s[2:3], s[4:5]
	s_mov_b64 exec, s[4:5]
	s_cbranch_execz .LBB0_5
	s_mov_b64 s[4:5], exec
	v_mbcnt_lo_u32_b32 v1, s4, 0
	v_mbcnt_hi_u32_b32 v1, s5, v1
	v_cmp_eq_u32_e32 vcc, 0, v1
	s_and_b64 s[8:9], exec, vcc
	s_mov_b64 exec, s[8:9]
	s_cbranch_execz .LBB0_5
	s_lshl_b32 s7, s6, 8
	s_bcnt1_i32_b64 s4, s[4:5]
	v_mov_b32_e32 v1, s7
	v_mov_b32_e32 v2, s4
	global_atomic_add v1, v2, s[14:15] offset:1024

.LBB0_351:
	v_lshrrev_b64 v[66:67], s24, v[110:111]
	v_and_b32_e32 v0, 1, v66
	v_cmp_eq_u32_e32 vcc, 1, v0
	s_mul_i32 s8, s19, 0x4800
	s_add_i32 s25, s8, 0
	v_cndmask_b32_e32 v88, -1, v192, vcc
	v_cmp_lt_i32_e64 s[10:11], -1, v88
	s_cmp_eq_u64 s[10:11], 0
	s_cselect_b64 s[20:21], -1, 0
	s_lshl_b32 s27, s24, 6
	s_cmp_gt_i32 s27, s61
	v_add_u32_e32 v0, s25, v170
	v_add_u32_e32 v86, s25, v171
	s_cselect_b64 s[24:25], -1, 0
	s_or_b64 s[24:25], s[20:21], s[24:25]
	v_cmp_gt_i32_e64 s[8:9], 0, v88
	s_and_b64 vcc, exec, s[24:25]
	v_add_u32_e32 v90, v0, v204
	s_cbranch_vccnz .LBB0_359
	ds_read_b128 v[66:69], v90
	ds_read_b128 v[92:95], v90 offset:32
	s_or_b32 s24, s27, 31
	s_cmp_le_i32 s24, s91
	s_mov_b64 s[24:25], -1
	s_waitcnt lgkmcnt(0)
	v_mfma_f32_32x32x16_bf16 v[66:81], v[66:69], v[114:117], 0
	v_mfma_f32_32x32x16_bf16 v[66:81], v[92:95], v[118:121], v[66:81]
	ds_read_b128 v[92:95], v90 offset:64
	s_waitcnt lgkmcnt(0)
	v_mfma_f32_32x32x16_bf16 v[66:81], v[92:95], v[126:129], v[66:81]
	ds_read_b128 v[92:95], v90 offset:96
	s_waitcnt lgkmcnt(0)
	v_mfma_f32_32x32x16_bf16 v[66:81], v[92:95], v[122:125], v[66:81]
	s_cbranch_scc0 .LBB0_369
	s_nop 10
	v_max3_f32 v0, v66, s72, v67
	v_max3_f32 v0, v0, v68, v69
	v_max3_f32 v0, v0, v70, v71
	v_max3_f32 v0, v0, v72, v73
	v_max3_f32 v0, v0, v74, v75
	v_max3_f32 v0, v0, v76, v77
	v_max3_f32 v0, v0, v78, v79
	v_mov_b32_e32 v89, v222
	v_max3_f32 v0, v0, v80, v81
	v_mul_f32_e32 v0, 0x3e38aa3b, v0
	v_lshlrev_b32_e32 v89, 2, v89
	v_cndmask_b32_e64 v0, v230, v0, s[10:11]
	v_xor_b32_e32 v89, 0x80, v89
	ds_bpermute_b32 v89, v89, v0
	s_waitcnt lgkmcnt(0)
	v_max3_f32 v89, v87, v0, v89
	v_cndmask_b32_e64 v221, -v230, v89, s[10:11]
	v_fma_f32 v0, v66, s36, -v221
	v_exp_f32_e32 v91, v0
	v_fma_f32 v0, v67, s36, -v221
	v_exp_f32_e32 v92, v0
	v_fma_f32 v0, v68, s36, -v221
	v_exp_f32_e32 v95, v0
	v_fma_f32 v0, v69, s36, -v221
	v_exp_f32_e32 v94, v0
	v_fma_f32 v93, v70, s36, -v221
	v_add_f32_e32 v0, 0, v91
	v_exp_f32_e32 v97, v93
	v_fma_f32 v93, v71, s36, -v221
	v_add_f32_e32 v0, v92, v0
	v_exp_f32_e32 v96, v93
	v_fma_f32 v93, v72, s36, -v221
	v_add_f32_e32 v0, v95, v0
	v_exp_f32_e32 v99, v93
	v_fma_f32 v93, v73, s36, -v221
	v_add_f32_e32 v0, v94, v0
	v_exp_f32_e32 v98, v93
	v_fma_f32 v93, v74, s36, -v221
	v_add_f32_e32 v0, v97, v0
	v_exp_f32_e32 v101, v93
	v_fma_f32 v93, v75, s36, -v221
	v_add_f32_e32 v0, v96, v0
	v_exp_f32_e32 v100, v93
	v_fma_f32 v93, v76, s36, -v221
	v_add_f32_e32 v0, v99, v0
	v_exp_f32_e32 v103, v93
	v_fma_f32 v93, v77, s36, -v221
	v_add_f32_e32 v0, v98, v0
	v_exp_f32_e32 v102, v93
	v_fma_f32 v93, v78, s36, -v221
	v_add_f32_e32 v0, v101, v0
	v_exp_f32_e32 v105, v93
	v_fma_f32 v93, v79, s36, -v221
	v_add_f32_e32 v0, v100, v0
	v_exp_f32_e32 v104, v93
	v_fma_f32 v93, v80, s36, -v221
	v_add_f32_e32 v0, v103, v0
	v_exp_f32_e32 v107, v93
	v_fma_f32 v93, v81, s36, -v221
	v_add_f32_e32 v0, v102, v0
	v_exp_f32_e32 v106, v93
	v_add_f32_e32 v0, v105, v0
	v_add_f32_e32 v0, v104, v0
	v_add_f32_e32 v0, v107, v0
	v_add_f32_e32 v93, v106, v0
	v_sub_f32_e32 v0, v87, v89
	v_exp_f32_e32 v0, v0
	s_cbranch_execz .LBB0_370

.LBB0_360:
	s_or_b32 s24, s27, 32
	s_cmp_gt_i32 s24, s61
	s_cselect_b64 s[28:29], -1, 0
	s_or_b64 s[20:21], s[20:21], s[28:29]
	s_and_b64 vcc, exec, s[20:21]
	s_cbranch_vccnz .LBB0_346
	ds_read_b128 v[66:69], v90 offset:4608
	ds_read_b128 v[92:95], v90 offset:4640
	s_or_b32 s20, s27, 63
	s_cmp_gt_i32 s20, s91
	s_mov_b64 s[20:21], -1
	s_waitcnt lgkmcnt(0)
	v_mfma_f32_32x32x16_bf16 v[66:81], v[66:69], v[114:117], 0
	v_mfma_f32_32x32x16_bf16 v[66:81], v[92:95], v[118:121], v[66:81]
	ds_read_b128 v[92:95], v90 offset:4672
	s_waitcnt lgkmcnt(0)
	v_mfma_f32_32x32x16_bf16 v[66:81], v[92:95], v[126:129], v[66:81]
	ds_read_b128 v[90:93], v90 offset:4704
	s_waitcnt lgkmcnt(0)
	v_mfma_f32_32x32x16_bf16 v[66:81], v[90:93], v[122:125], v[66:81]
	s_cbranch_scc1 .LBB0_371
	s_nop 10
	v_max3_f32 v0, v66, s72, v67
	v_max3_f32 v0, v0, v68, v69
	v_max3_f32 v0, v0, v70, v71
	v_max3_f32 v0, v0, v72, v73
	v_max3_f32 v0, v0, v74, v75
	v_max3_f32 v0, v0, v76, v77
	v_max3_f32 v0, v0, v78, v79
	v_mov_b32_e32 v87, v222
	v_max3_f32 v0, v0, v80, v81
	v_mul_f32_e32 v0, 0x3e38aa3b, v0
	v_lshlrev_b32_e32 v87, 2, v87
	v_cndmask_b32_e64 v0, v230, v0, s[10:11]
	v_xor_b32_e32 v87, 0x80, v87
	ds_bpermute_b32 v87, v87, v0
	s_waitcnt lgkmcnt(0)
	v_max3_f32 v87, v89, v0, v87
	v_cndmask_b32_e64 v221, -v230, v87, s[10:11]
	v_fma_f32 v0, v66, s36, -v221
	v_exp_f32_e32 v90, v0
	v_fma_f32 v0, v67, s36, -v221
	v_exp_f32_e32 v91, v0
	v_fma_f32 v0, v68, s36, -v221
	v_exp_f32_e32 v94, v0
	v_fma_f32 v0, v69, s36, -v221
	v_exp_f32_e32 v93, v0
	v_fma_f32 v92, v70, s36, -v221
	v_add_f32_e32 v0, 0, v90
	v_exp_f32_e32 v96, v92
	v_fma_f32 v92, v71, s36, -v221
	v_add_f32_e32 v0, v91, v0
	v_exp_f32_e32 v95, v92
	v_fma_f32 v92, v72, s36, -v221
	v_add_f32_e32 v0, v94, v0
	v_exp_f32_e32 v98, v92
	v_fma_f32 v92, v73, s36, -v221
	v_add_f32_e32 v0, v93, v0
	v_exp_f32_e32 v97, v92
	v_fma_f32 v92, v74, s36, -v221
	v_add_f32_e32 v0, v96, v0
	v_exp_f32_e32 v100, v92
	v_fma_f32 v92, v75, s36, -v221
	v_add_f32_e32 v0, v95, v0
	v_exp_f32_e32 v99, v92
	v_fma_f32 v92, v76, s36, -v221
	v_add_f32_e32 v0, v98, v0
	v_exp_f32_e32 v102, v92
	v_fma_f32 v92, v77, s36, -v221
	v_add_f32_e32 v0, v97, v0
	v_exp_f32_e32 v101, v92
	v_fma_f32 v92, v78, s36, -v221
	v_add_f32_e32 v0, v100, v0
	v_exp_f32_e32 v104, v92
	v_fma_f32 v92, v79, s36, -v221
	v_add_f32_e32 v0, v99, v0
	v_exp_f32_e32 v103, v92
	v_fma_f32 v92, v80, s36, -v221
	v_add_f32_e32 v0, v102, v0
	v_exp_f32_e32 v106, v92
	v_fma_f32 v92, v81, s36, -v221
	v_add_f32_e32 v0, v101, v0
	v_exp_f32_e32 v105, v92
	v_add_f32_e32 v0, v104, v0
	v_add_f32_e32 v0, v103, v0
	v_add_f32_e32 v0, v106, v0
	v_add_f32_e32 v92, v105, v0
	v_sub_f32_e32 v0, v89, v87
	v_exp_f32_e32 v0, v0
	s_cbranch_execz .LBB0_372

.Lprio_skip_gu:
.LBB0_960:
	s_add_u32 s24, s20, 0xfffc0080
	s_addc_u32 s25, s21, -1
	s_add_i32 s72, 0, 0x10000
	s_cmp_eq_u32 s71, 12
	s_cselect_b32 s27, s11, s25
	s_cselect_b32 s26, s67, s24
	v_add_u32_e32 v140, s72, v143
	s_cselect_b32 s25, s7, s70
	s_cselect_b32 s24, s68, s69
	s_add_i32 s74, 0, 0x14000
	ds_read_b128 v[148:151], v140
	ds_read_b128 v[152:155], v140 offset:1024
	ds_read_b128 v[170:173], v140 offset:2048
	ds_read_b128 v[174:177], v140 offset:3072
	v_add_u32_e32 v140, s74, v143
	ds_read_b128 v[178:181], v140
	ds_read_b128 v[182:185], v140 offset:1024
	ds_read_b128 v[186:189], v140 offset:2048
	ds_read_b128 v[190:193], v140 offset:3072
	v_lshl_add_u64 v[140:141], s[20:21], 0, v[138:139]
	s_add_i32 m0, s34, 0xc000
	ds_read_b128 v[194:197], v146
	ds_read_b128 v[198:201], v146 offset:1024
	ds_read_b128 v[206:209], v146 offset:2048
	ds_read_b128 v[210:213], v146 offset:3072
	ds_read_b128 v[214:217], v146 offset:4096
	ds_read_b128 v[238:241], v146 offset:5120
	ds_read_b128 v[242:245], v146 offset:6144
	ds_read_b128 v[246:249], v146 offset:7168
	global_load_lds_dwordx4 v[140:141], off
	v_lshl_add_u64 v[140:141], s[20:21], 0, v[136:137]
	s_add_i32 m0, s34, 0xe000
	s_nop 0
	global_load_lds_dwordx4 v[140:141], off
	s_cmp_eq_u32 s71, -2
	s_cbranch_scc0 .Lgu_v8
	s_cmp_eq_u32 s100, 0
	s_cbranch_scc1 .Lgu_v8
	s_waitcnt vmcnt(16)
	s_branch .Lgu_vd
.Lgu_v8:
	s_waitcnt vmcnt(8)
.Lgu_vd:
	s_waitcnt lgkmcnt(0)
	s_barrier
	s_waitcnt lgkmcnt(0)
	v_mfma_f32_16x16x32_bf16 v[126:129], v[148:151], v[194:197], v[126:129]
	v_mfma_f32_16x16x32_bf16 v[118:121], v[170:173], v[194:197], v[118:121]
	v_mfma_f32_16x16x32_bf16 v[110:113], v[148:151], v[206:209], v[110:113]
	v_mfma_f32_16x16x32_bf16 v[102:105], v[170:173], v[206:209], v[102:105]
	v_mfma_f32_16x16x32_bf16 v[94:97], v[148:151], v[214:217], v[94:97]
	v_mfma_f32_16x16x32_bf16 v[86:89], v[170:173], v[214:217], v[86:89]
	v_mfma_f32_16x16x32_bf16 v[78:81], v[148:151], v[242:245], v[78:81]
	v_mfma_f32_16x16x32_bf16 v[70:73], v[170:173], v[242:245], v[70:73]
	v_mfma_f32_16x16x32_bf16 v[126:129], v[152:155], v[198:201], v[126:129]
	v_mfma_f32_16x16x32_bf16 v[118:121], v[174:177], v[198:201], v[118:121]
	v_mfma_f32_16x16x32_bf16 v[110:113], v[152:155], v[210:213], v[110:113]
	v_mfma_f32_16x16x32_bf16 v[102:105], v[174:177], v[210:213], v[102:105]
	v_mfma_f32_16x16x32_bf16 v[94:97], v[152:155], v[238:241], v[94:97]
	v_mfma_f32_16x16x32_bf16 v[86:89], v[174:177], v[238:241], v[86:89]
	v_mfma_f32_16x16x32_bf16 v[78:81], v[152:155], v[246:249], v[78:81]
	v_mfma_f32_16x16x32_bf16 v[70:73], v[174:177], v[246:249], v[70:73]
	v_mfma_f32_16x16x32_bf16 v[122:125], v[178:181], v[194:197], v[122:125]
	v_mfma_f32_16x16x32_bf16 v[114:117], v[186:189], v[194:197], v[114:117]
	v_mfma_f32_16x16x32_bf16 v[106:109], v[178:181], v[206:209], v[106:109]
	v_mfma_f32_16x16x32_bf16 v[98:101], v[186:189], v[206:209], v[98:101]
	v_mfma_f32_16x16x32_bf16 v[90:93], v[178:181], v[214:217], v[90:93]
	v_mfma_f32_16x16x32_bf16 v[82:85], v[186:189], v[214:217], v[82:85]
	v_mfma_f32_16x16x32_bf16 v[74:77], v[178:181], v[242:245], v[74:77]
	v_mfma_f32_16x16x32_bf16 v[66:69], v[186:189], v[242:245], v[66:69]
	v_mfma_f32_16x16x32_bf16 v[122:125], v[182:185], v[198:201], v[122:125]
	v_mfma_f32_16x16x32_bf16 v[114:117], v[190:193], v[198:201], v[114:117]
	v_mfma_f32_16x16x32_bf16 v[106:109], v[182:185], v[210:213], v[106:109]
	v_mfma_f32_16x16x32_bf16 v[98:101], v[190:193], v[210:213], v[98:101]
	v_mfma_f32_16x16x32_bf16 v[90:93], v[182:185], v[238:241], v[90:93]
	v_mfma_f32_16x16x32_bf16 v[82:85], v[190:193], v[238:241], v[82:85]
	v_mfma_f32_16x16x32_bf16 v[74:77], v[182:185], v[246:249], v[74:77]
	v_mfma_f32_16x16x32_bf16 v[66:69], v[190:193], v[246:249], v[66:69]
	s_barrier
	s_add_i32 s72, s72, s18
	v_lshl_add_u64 v[140:141], s[24:25], 0, v[0:1]
	s_mov_b32 m0, s72
	ds_read_b128 v[194:197], v146 offset:16384
	ds_read_b128 v[198:201], v146 offset:17408
	ds_read_b128 v[206:209], v146 offset:18432
	ds_read_b128 v[210:213], v146 offset:19456
	ds_read_b128 v[214:217], v146 offset:20480
	ds_read_b128 v[238:241], v146 offset:21504
	ds_read_b128 v[242:245], v146 offset:22528
	ds_read_b128 v[246:249], v146 offset:23552
	global_load_lds_dwordx4 v[140:141], off
	s_add_i32 m0, s72, 0x2000
	s_add_u32 s72, s24, 0x40000
	v_lshl_add_u64 v[156:157], s[24:25], 0, v[130:131]
	s_addc_u32 s73, s25, 0
	s_add_i32 s74, s74, s18
	global_load_lds_dwordx4 v[156:157], off
	v_lshl_add_u64 v[202:203], s[72:73], 0, v[0:1]
	s_mov_b32 m0, s74
	v_lshl_add_u64 v[250:251], s[26:27], 0, v[132:133]
	global_load_lds_dwordx4 v[202:203], off
	v_lshl_add_u64 v[202:203], s[72:73], 0, v[130:131]
	s_add_i32 m0, s74, 0x2000
	s_nop 0
	global_load_lds_dwordx4 v[202:203], off
	v_lshl_add_u64 v[202:203], s[26:27], 0, v[134:135]
	s_mov_b32 m0, s34
	s_nop 0
	global_load_lds_dwordx4 v[202:203], off
	s_mov_b32 m0, s35
	s_nop 0
	global_load_lds_dwordx4 v[250:251], off
	s_cmp_eq_u32 s71, -2
	s_cbranch_scc0 .Lgu_w8
	s_cmp_eq_u32 s100, 0
	s_cbranch_scc1 .Lgu_w8
	s_mov_b32 s100, 0
	s_waitcnt vmcnt(16)
	s_branch .Lgu_wd

.Lgu_wd:
	s_waitcnt lgkmcnt(0)
	s_barrier
	s_waitcnt lgkmcnt(0)
	v_mfma_f32_16x16x32_bf16 v[62:65], v[148:151], v[194:197], v[62:65]
	v_mfma_f32_16x16x32_bf16 v[54:57], v[170:173], v[194:197], v[54:57]
	v_mfma_f32_16x16x32_bf16 v[46:49], v[148:151], v[206:209], v[46:49]
	v_mfma_f32_16x16x32_bf16 v[38:41], v[170:173], v[206:209], v[38:41]
	v_mfma_f32_16x16x32_bf16 v[30:33], v[148:151], v[214:217], v[30:33]
	v_mfma_f32_16x16x32_bf16 v[22:25], v[170:173], v[214:217], v[22:25]
	v_mfma_f32_16x16x32_bf16 v[14:17], v[148:151], v[242:245], v[14:17]
	v_mfma_f32_16x16x32_bf16 v[6:9], v[170:173], v[242:245], v[6:9]
	v_mfma_f32_16x16x32_bf16 v[62:65], v[152:155], v[198:201], v[62:65]
	v_mfma_f32_16x16x32_bf16 v[54:57], v[174:177], v[198:201], v[54:57]
	v_mfma_f32_16x16x32_bf16 v[46:49], v[152:155], v[210:213], v[46:49]
	v_mfma_f32_16x16x32_bf16 v[38:41], v[174:177], v[210:213], v[38:41]
	v_mfma_f32_16x16x32_bf16 v[30:33], v[152:155], v[238:241], v[30:33]
	v_mfma_f32_16x16x32_bf16 v[22:25], v[174:177], v[238:241], v[22:25]
	v_mfma_f32_16x16x32_bf16 v[14:17], v[152:155], v[246:249], v[14:17]
	v_mfma_f32_16x16x32_bf16 v[6:9], v[174:177], v[246:249], v[6:9]
	v_mfma_f32_16x16x32_bf16 v[58:61], v[178:181], v[194:197], v[58:61]
	v_mfma_f32_16x16x32_bf16 v[50:53], v[186:189], v[194:197], v[50:53]
	v_mfma_f32_16x16x32_bf16 v[42:45], v[178:181], v[206:209], v[42:45]
	v_mfma_f32_16x16x32_bf16 v[34:37], v[186:189], v[206:209], v[34:37]
	v_mfma_f32_16x16x32_bf16 v[26:29], v[178:181], v[214:217], v[26:29]
	v_mfma_f32_16x16x32_bf16 v[18:21], v[186:189], v[214:217], v[18:21]
	v_mfma_f32_16x16x32_bf16 v[10:13], v[178:181], v[242:245], v[10:13]
	v_mfma_f32_16x16x32_bf16 v[2:5], v[186:189], v[242:245], v[2:5]
	v_mfma_f32_16x16x32_bf16 v[58:61], v[182:185], v[198:201], v[58:61]
	v_mfma_f32_16x16x32_bf16 v[50:53], v[190:193], v[198:201], v[50:53]
	v_mfma_f32_16x16x32_bf16 v[42:45], v[182:185], v[210:213], v[42:45]
	v_mfma_f32_16x16x32_bf16 v[34:37], v[190:193], v[210:213], v[34:37]
	v_mfma_f32_16x16x32_bf16 v[26:29], v[182:185], v[238:241], v[26:29]
	v_mfma_f32_16x16x32_bf16 v[18:21], v[190:193], v[238:241], v[18:21]
	v_mfma_f32_16x16x32_bf16 v[10:13], v[182:185], v[246:249], v[10:13]
	v_mfma_f32_16x16x32_bf16 v[2:5], v[190:193], v[246:249], v[2:5]
	s_barrier
	s_add_i32 s72, 0, 0x18000
	v_add_u32_e32 v147, s72, v143
	s_add_i32 s73, 0, 0x1c000
	ds_read_b128 v[148:151], v147
	ds_read_b128 v[152:155], v147 offset:1024
	ds_read_b128 v[170:173], v147 offset:2048
	ds_read_b128 v[174:177], v147 offset:3072
	v_add_u32_e32 v147, s73, v143
	ds_read_b128 v[178:181], v147
	ds_read_b128 v[182:185], v147 offset:1024
	ds_read_b128 v[186:189], v147 offset:2048
	ds_read_b128 v[190:193], v147 offset:3072
	s_add_u32 s26, s26, 0x40000
	s_addc_u32 s27, s27, 0
	s_mov_b32 m0, s38
	v_lshl_add_u64 v[220:221], s[26:27], 0, v[134:135]
	ds_read_b128 v[194:197], v146 offset:32768
	ds_read_b128 v[198:201], v146 offset:33792
	ds_read_b128 v[206:209], v146 offset:34816
	ds_read_b128 v[210:213], v146 offset:35840
	ds_read_b128 v[214:217], v146 offset:36864
	ds_read_b128 v[238:241], v146 offset:37888
	ds_read_b128 v[242:245], v146 offset:38912
	ds_read_b128 v[246:249], v146 offset:39936
	global_load_lds_dwordx4 v[220:221], off
	v_lshl_add_u64 v[220:221], s[26:27], 0, v[132:133]
	s_mov_b32 m0, s39
	s_nop 0
	global_load_lds_dwordx4 v[220:221], off
	s_waitcnt vmcnt(8)
	s_waitcnt lgkmcnt(0)
	s_barrier
	s_waitcnt lgkmcnt(0)
	v_mfma_f32_16x16x32_bf16 v[126:129], v[148:151], v[194:197], v[126:129]
	v_mfma_f32_16x16x32_bf16 v[118:121], v[170:173], v[194:197], v[118:121]
	v_mfma_f32_16x16x32_bf16 v[110:113], v[148:151], v[206:209], v[110:113]
	v_mfma_f32_16x16x32_bf16 v[102:105], v[170:173], v[206:209], v[102:105]
	v_mfma_f32_16x16x32_bf16 v[94:97], v[148:151], v[214:217], v[94:97]
	v_mfma_f32_16x16x32_bf16 v[86:89], v[170:173], v[214:217], v[86:89]
	v_mfma_f32_16x16x32_bf16 v[78:81], v[148:151], v[242:245], v[78:81]
	v_mfma_f32_16x16x32_bf16 v[70:73], v[170:173], v[242:245], v[70:73]
	v_mfma_f32_16x16x32_bf16 v[126:129], v[152:155], v[198:201], v[126:129]
	v_mfma_f32_16x16x32_bf16 v[118:121], v[174:177], v[198:201], v[118:121]
	v_mfma_f32_16x16x32_bf16 v[110:113], v[152:155], v[210:213], v[110:113]
	v_mfma_f32_16x16x32_bf16 v[102:105], v[174:177], v[210:213], v[102:105]
	v_mfma_f32_16x16x32_bf16 v[94:97], v[152:155], v[238:241], v[94:97]
	v_mfma_f32_16x16x32_bf16 v[86:89], v[174:177], v[238:241], v[86:89]
	v_mfma_f32_16x16x32_bf16 v[78:81], v[152:155], v[246:249], v[78:81]
	v_mfma_f32_16x16x32_bf16 v[70:73], v[174:177], v[246:249], v[70:73]
	v_mfma_f32_16x16x32_bf16 v[122:125], v[178:181], v[194:197], v[122:125]
	v_mfma_f32_16x16x32_bf16 v[114:117], v[186:189], v[194:197], v[114:117]
	v_mfma_f32_16x16x32_bf16 v[106:109], v[178:181], v[206:209], v[106:109]
	v_mfma_f32_16x16x32_bf16 v[98:101], v[186:189], v[206:209], v[98:101]
	v_mfma_f32_16x16x32_bf16 v[90:93], v[178:181], v[214:217], v[90:93]
	v_mfma_f32_16x16x32_bf16 v[82:85], v[186:189], v[214:217], v[82:85]
	v_mfma_f32_16x16x32_bf16 v[74:77], v[178:181], v[242:245], v[74:77]
	v_mfma_f32_16x16x32_bf16 v[66:69], v[186:189], v[242:245], v[66:69]
	v_mfma_f32_16x16x32_bf16 v[122:125], v[182:185], v[198:201], v[122:125]
	v_mfma_f32_16x16x32_bf16 v[114:117], v[190:193], v[198:201], v[114:117]
	v_mfma_f32_16x16x32_bf16 v[106:109], v[182:185], v[210:213], v[106:109]
	v_mfma_f32_16x16x32_bf16 v[98:101], v[190:193], v[210:213], v[98:101]
	v_mfma_f32_16x16x32_bf16 v[90:93], v[182:185], v[238:241], v[90:93]
	v_mfma_f32_16x16x32_bf16 v[82:85], v[190:193], v[238:241], v[82:85]
	v_mfma_f32_16x16x32_bf16 v[74:77], v[182:185], v[246:249], v[74:77]
	v_mfma_f32_16x16x32_bf16 v[66:69], v[190:193], v[246:249], v[66:69]
	s_barrier
	s_add_i32 s26, s72, s18
	v_lshl_add_u64 v[140:141], v[140:141], 0, s[22:23]
	s_mov_b32 m0, s26
	ds_read_b128 v[194:197], v146 offset:49152
	ds_read_b128 v[198:201], v146 offset:50176
	ds_read_b128 v[206:209], v146 offset:51200
	ds_read_b128 v[210:213], v146 offset:52224
	ds_read_b128 v[214:217], v146 offset:53248
	ds_read_b128 v[238:241], v146 offset:54272
	ds_read_b128 v[242:245], v146 offset:55296
	ds_read_b128 v[246:249], v146 offset:56320
	global_load_lds_dwordx4 v[140:141], off
	s_add_i32 m0, s26, 0x2000
	s_add_u32 s24, s24, 0x40080
	v_lshl_add_u64 v[140:141], v[156:157], 0, s[22:23]
	s_addc_u32 s25, s25, 0
	s_add_i32 s26, s73, s18
	global_load_lds_dwordx4 v[140:141], off
	v_lshl_add_u64 v[140:141], s[24:25], 0, v[0:1]
	s_mov_b32 m0, s26
	s_nop 0
	global_load_lds_dwordx4 v[140:141], off
	v_lshl_add_u64 v[140:141], s[24:25], 0, v[130:131]
	s_add_i32 m0, s26, 0x2000
	s_nop 0
	global_load_lds_dwordx4 v[140:141], off
	v_lshl_add_u64 v[140:141], v[202:203], 0, s[22:23]
	s_mov_b32 m0, s57
	s_nop 0
	global_load_lds_dwordx4 v[140:141], off
	v_lshl_add_u64 v[140:141], v[250:251], 0, s[22:23]
	s_mov_b32 m0, s61
	s_nop 0
	global_load_lds_dwordx4 v[140:141], off
	s_waitcnt vmcnt(8)
	s_waitcnt lgkmcnt(0)
	s_barrier
	s_waitcnt lgkmcnt(0)
	v_mfma_f32_16x16x32_bf16 v[62:65], v[148:151], v[194:197], v[62:65]
	v_mfma_f32_16x16x32_bf16 v[54:57], v[170:173], v[194:197], v[54:57]
	v_mfma_f32_16x16x32_bf16 v[46:49], v[148:151], v[206:209], v[46:49]
	v_mfma_f32_16x16x32_bf16 v[38:41], v[170:173], v[206:209], v[38:41]
	v_mfma_f32_16x16x32_bf16 v[30:33], v[148:151], v[214:217], v[30:33]
	v_mfma_f32_16x16x32_bf16 v[22:25], v[170:173], v[214:217], v[22:25]
	v_mfma_f32_16x16x32_bf16 v[14:17], v[148:151], v[242:245], v[14:17]
	v_mfma_f32_16x16x32_bf16 v[6:9], v[170:173], v[242:245], v[6:9]
	v_mfma_f32_16x16x32_bf16 v[62:65], v[152:155], v[198:201], v[62:65]
	v_mfma_f32_16x16x32_bf16 v[54:57], v[174:177], v[198:201], v[54:57]
	v_mfma_f32_16x16x32_bf16 v[46:49], v[152:155], v[210:213], v[46:49]
	v_mfma_f32_16x16x32_bf16 v[38:41], v[174:177], v[210:213], v[38:41]
	v_mfma_f32_16x16x32_bf16 v[30:33], v[152:155], v[238:241], v[30:33]
	v_mfma_f32_16x16x32_bf16 v[22:25], v[174:177], v[238:241], v[22:25]
	v_mfma_f32_16x16x32_bf16 v[14:17], v[152:155], v[246:249], v[14:17]
	v_mfma_f32_16x16x32_bf16 v[6:9], v[174:177], v[246:249], v[6:9]
	v_mfma_f32_16x16x32_bf16 v[58:61], v[178:181], v[194:197], v[58:61]
	v_mfma_f32_16x16x32_bf16 v[50:53], v[186:189], v[194:197], v[50:53]
	v_mfma_f32_16x16x32_bf16 v[42:45], v[178:181], v[206:209], v[42:45]
	v_mfma_f32_16x16x32_bf16 v[34:37], v[186:189], v[206:209], v[34:37]
	v_mfma_f32_16x16x32_bf16 v[26:29], v[178:181], v[214:217], v[26:29]
	v_mfma_f32_16x16x32_bf16 v[18:21], v[186:189], v[214:217], v[18:21]
	v_mfma_f32_16x16x32_bf16 v[10:13], v[178:181], v[242:245], v[10:13]
	v_mfma_f32_16x16x32_bf16 v[2:5], v[186:189], v[242:245], v[2:5]
	v_mfma_f32_16x16x32_bf16 v[58:61], v[182:185], v[198:201], v[58:61]
	v_mfma_f32_16x16x32_bf16 v[50:53], v[190:193], v[198:201], v[50:53]
	v_mfma_f32_16x16x32_bf16 v[42:45], v[182:185], v[210:213], v[42:45]
	v_mfma_f32_16x16x32_bf16 v[34:37], v[190:193], v[210:213], v[34:37]
	v_mfma_f32_16x16x32_bf16 v[26:29], v[182:185], v[238:241], v[26:29]
	v_mfma_f32_16x16x32_bf16 v[18:21], v[190:193], v[238:241], v[18:21]
	v_mfma_f32_16x16x32_bf16 v[10:13], v[182:185], v[246:249], v[10:13]
	v_mfma_f32_16x16x32_bf16 v[2:5], v[190:193], v[246:249], v[2:5]
	s_barrier
	s_add_i32 s71, s71, 2
	s_add_u32 s69, s69, 0x100
	s_addc_u32 s70, s70, 0
	s_add_u32 s20, s20, 0x100
	s_addc_u32 s21, s21, 0
	s_cmp_gt_u32 s71, 13
	s_cbranch_scc0 .LBB0_960
	s_setprio 0
	s_and_b64 vcc, exec, s[4:5]
	s_cbranch_vccz .LBB0_963
	s_barrier
.LBB0_963:
	v_lshl_add_u32 v148, s66, 10, v145
	ds_read_b32 v154, v148
	s_mov_b32 s20, 0xbfb8aa3b
	v_lshl_or_b32 v150, s9, 7, v144
	v_lshl_add_u32 v147, s8, 8, v142
	v_readlane_b32 s8, v254, 35
	s_waitcnt lgkmcnt(0)
	v_pk_mul_f32 v[126:127], v[126:127], v[154:155] op_sel_hi:[1,0]
	v_pk_mul_f32 v[122:123], v[122:123], v[154:155] op_sel_hi:[1,0]
	v_pk_mul_f32 v[156:157], v[126:127], s[20:21] op_sel_hi:[1,0]
	v_pk_mul_f32 v[124:125], v[124:125], v[154:155] op_sel_hi:[1,0]
	v_exp_f32_e32 v156, v156
	v_exp_f32_e32 v157, v157
	v_pk_mul_f32 v[118:119], v[118:119], v[154:155] op_sel_hi:[1,0]
	v_pk_mul_f32 v[114:115], v[114:115], v[154:155] op_sel_hi:[1,0]
	v_readlane_b32 s9, v254, 36
	v_pk_add_f32 v[156:157], v[156:157], 1.0 op_sel_hi:[1,0]
	v_pk_mul_f32 v[116:117], v[116:117], v[154:155] op_sel_hi:[1,0]
	v_rcp_f32_e32 v156, v156
	v_rcp_f32_e32 v157, v157
	v_ashrrev_i32_e32 v151, 31, v150
	v_mov_b64_e32 v[140:141], s[8:9]
	s_movk_i32 s7, 0x1600
	v_pk_mul_f32 v[126:127], v[126:127], v[156:157]
	v_mad_i64_i32 v[152:153], s[8:9], v147, s7, v[140:141]
	v_pk_mul_f32 v[122:123], v[122:123], v[126:127]
	v_pk_mul_f32 v[126:127], v[128:129], v[154:155] op_sel_hi:[1,0]
	v_cvt_pk_bf16_f32 v122, v122, v123
	s_andn2_b64 vcc, exec, s[2:3]
	v_pk_mul_f32 v[128:129], v[126:127], s[20:21] op_sel_hi:[1,0]
	s_mov_b32 s72, 0xf149f2ca
	v_exp_f32_e32 v128, v128
	v_exp_f32_e32 v129, v129
	s_nop 0
	v_pk_add_f32 v[128:129], v[128:129], 1.0 op_sel_hi:[1,0]
	s_nop 0
	v_rcp_f32_e32 v128, v128
	v_rcp_f32_e32 v129, v129
	s_nop 0
	v_pk_mul_f32 v[126:127], v[126:127], v[128:129]
	s_nop 0
	v_pk_mul_f32 v[124:125], v[124:125], v[126:127]
	s_nop 0
	v_cvt_pk_bf16_f32 v123, v124, v125
	v_pk_mul_f32 v[124:125], v[118:119], s[20:21] op_sel_hi:[1,0]
	s_nop 0
	v_exp_f32_e32 v124, v124
	v_exp_f32_e32 v125, v125
	s_nop 0
	v_pk_add_f32 v[124:125], v[124:125], 1.0 op_sel_hi:[1,0]
	s_nop 0
	v_rcp_f32_e32 v124, v124
	v_rcp_f32_e32 v125, v125
	s_nop 0
	v_pk_mul_f32 v[118:119], v[118:119], v[124:125]
	s_nop 0
	v_pk_mul_f32 v[114:115], v[114:115], v[118:119]
	s_nop 0
	v_cvt_pk_bf16_f32 v124, v114, v115
	v_pk_mul_f32 v[114:115], v[120:121], v[154:155] op_sel_hi:[1,0]
	s_nop 0
	v_pk_mul_f32 v[118:119], v[114:115], s[20:21] op_sel_hi:[1,0]
	s_nop 0
	v_exp_f32_e32 v118, v118
	v_exp_f32_e32 v119, v119
	s_nop 0
	v_pk_add_f32 v[118:119], v[118:119], 1.0 op_sel_hi:[1,0]
	s_nop 0
	v_rcp_f32_e32 v118, v118
	v_rcp_f32_e32 v119, v119
	s_nop 0
	v_pk_mul_f32 v[114:115], v[114:115], v[118:119]
	s_nop 0
	v_pk_mul_f32 v[114:115], v[116:117], v[114:115]
	s_nop 0
	v_cvt_pk_bf16_f32 v125, v114, v115
	v_lshlrev_b64 v[114:115], 1, v[150:151]
	v_lshl_add_u64 v[116:117], v[152:153], 0, v[114:115]
	global_store_dwordx4 v[116:117], v[122:125], off
	ds_read_b32 v118, v148 offset:64
	v_or_b32_e32 v116, 16, v147
	v_mad_i64_i32 v[116:117], s[8:9], v116, s7, v[140:141]
	s_waitcnt lgkmcnt(0)
	v_pk_mul_f32 v[110:111], v[110:111], v[118:119] op_sel_hi:[1,0]
	s_nop 0
	v_pk_mul_f32 v[120:121], v[110:111], s[20:21] op_sel_hi:[1,0]
	v_pk_mul_f32 v[106:107], v[106:107], v[118:119] op_sel_hi:[1,0]
	v_exp_f32_e32 v120, v120
	v_exp_f32_e32 v121, v121
	v_pk_mul_f32 v[108:109], v[108:109], v[118:119] op_sel_hi:[1,0]
	v_pk_mul_f32 v[102:103], v[102:103], v[118:119] op_sel_hi:[1,0]
	v_pk_mul_f32 v[98:99], v[98:99], v[118:119] op_sel_hi:[1,0]
	v_pk_add_f32 v[120:121], v[120:121], 1.0 op_sel_hi:[1,0]
	v_pk_mul_f32 v[100:101], v[100:101], v[118:119] op_sel_hi:[1,0]
	v_rcp_f32_e32 v120, v120
	v_rcp_f32_e32 v121, v121
	s_nop 0
	v_pk_mul_f32 v[110:111], v[110:111], v[120:121]
	s_nop 0
	v_pk_mul_f32 v[106:107], v[106:107], v[110:111]
	v_pk_mul_f32 v[110:111], v[112:113], v[118:119] op_sel_hi:[1,0]
	v_cvt_pk_bf16_f32 v106, v106, v107
	s_nop 0
	v_pk_mul_f32 v[112:113], v[110:111], s[20:21] op_sel_hi:[1,0]
	s_nop 0
	v_exp_f32_e32 v112, v112
	v_exp_f32_e32 v113, v113
	s_nop 0
	v_pk_add_f32 v[112:113], v[112:113], 1.0 op_sel_hi:[1,0]
	s_nop 0
	v_rcp_f32_e32 v112, v112
	v_rcp_f32_e32 v113, v113
	s_nop 0
	v_pk_mul_f32 v[110:111], v[110:111], v[112:113]
	s_nop 0
	v_pk_mul_f32 v[108:109], v[108:109], v[110:111]
	s_nop 0
	v_cvt_pk_bf16_f32 v107, v108, v109
	v_pk_mul_f32 v[108:109], v[102:103], s[20:21] op_sel_hi:[1,0]
	s_nop 0
	v_exp_f32_e32 v108, v108
	v_exp_f32_e32 v109, v109
	s_nop 0
	v_pk_add_f32 v[108:109], v[108:109], 1.0 op_sel_hi:[1,0]
	s_nop 0
	v_rcp_f32_e32 v108, v108
	v_rcp_f32_e32 v109, v109
	s_nop 0
	v_pk_mul_f32 v[102:103], v[102:103], v[108:109]
	s_nop 0
	v_pk_mul_f32 v[98:99], v[98:99], v[102:103]
	s_nop 0
	v_cvt_pk_bf16_f32 v108, v98, v99
	v_pk_mul_f32 v[98:99], v[104:105], v[118:119] op_sel_hi:[1,0]
	s_nop 0
	v_pk_mul_f32 v[102:103], v[98:99], s[20:21] op_sel_hi:[1,0]
	s_nop 0
	v_exp_f32_e32 v102, v102
	v_exp_f32_e32 v103, v103
	s_nop 0
	v_pk_add_f32 v[102:103], v[102:103], 1.0 op_sel_hi:[1,0]
	s_nop 0
	v_rcp_f32_e32 v102, v102
	v_rcp_f32_e32 v103, v103
	s_nop 0
	v_pk_mul_f32 v[98:99], v[98:99], v[102:103]
	s_nop 0
	v_pk_mul_f32 v[98:99], v[100:101], v[98:99]
	s_nop 0
	v_cvt_pk_bf16_f32 v109, v98, v99
	v_lshl_add_u64 v[98:99], v[116:117], 0, v[114:115]
	global_store_dwordx4 v[98:99], v[106:109], off
	ds_read_b32 v100, v148 offset:128
	v_or_b32_e32 v98, 32, v147
	v_mad_i64_i32 v[98:99], s[8:9], v98, s7, v[140:141]
	s_waitcnt lgkmcnt(0)
	v_pk_mul_f32 v[94:95], v[94:95], v[100:101] op_sel_hi:[1,0]
	s_nop 0
	v_pk_mul_f32 v[102:103], v[94:95], s[20:21] op_sel_hi:[1,0]
	v_pk_mul_f32 v[90:91], v[90:91], v[100:101] op_sel_hi:[1,0]
	v_exp_f32_e32 v102, v102
	v_exp_f32_e32 v103, v103
	v_pk_mul_f32 v[92:93], v[92:93], v[100:101] op_sel_hi:[1,0]
	v_pk_mul_f32 v[86:87], v[86:87], v[100:101] op_sel_hi:[1,0]
	v_pk_mul_f32 v[82:83], v[82:83], v[100:101] op_sel_hi:[1,0]
	v_pk_add_f32 v[102:103], v[102:103], 1.0 op_sel_hi:[1,0]
	v_pk_mul_f32 v[84:85], v[84:85], v[100:101] op_sel_hi:[1,0]
	v_rcp_f32_e32 v102, v102
	v_rcp_f32_e32 v103, v103
	s_nop 0
	v_pk_mul_f32 v[94:95], v[94:95], v[102:103]
	s_nop 0
	v_pk_mul_f32 v[90:91], v[90:91], v[94:95]
	v_pk_mul_f32 v[94:95], v[96:97], v[100:101] op_sel_hi:[1,0]
	v_cvt_pk_bf16_f32 v90, v90, v91
	s_nop 0
	v_pk_mul_f32 v[96:97], v[94:95], s[20:21] op_sel_hi:[1,0]
	s_nop 0
	v_exp_f32_e32 v96, v96
	v_exp_f32_e32 v97, v97
	s_nop 0
	v_pk_add_f32 v[96:97], v[96:97], 1.0 op_sel_hi:[1,0]
	s_nop 0
	v_rcp_f32_e32 v96, v96
	v_rcp_f32_e32 v97, v97
	s_nop 0
	v_pk_mul_f32 v[94:95], v[94:95], v[96:97]
	s_nop 0
	v_pk_mul_f32 v[92:93], v[92:93], v[94:95]
	s_nop 0
	v_cvt_pk_bf16_f32 v91, v92, v93
	v_pk_mul_f32 v[92:93], v[86:87], s[20:21] op_sel_hi:[1,0]
	s_nop 0
	v_exp_f32_e32 v92, v92
	v_exp_f32_e32 v93, v93
	s_nop 0
	v_pk_add_f32 v[92:93], v[92:93], 1.0 op_sel_hi:[1,0]
	s_nop 0
	v_rcp_f32_e32 v92, v92
	v_rcp_f32_e32 v93, v93
	s_nop 0
	v_pk_mul_f32 v[86:87], v[86:87], v[92:93]
	s_nop 0
	v_pk_mul_f32 v[82:83], v[82:83], v[86:87]
	s_nop 0
	v_cvt_pk_bf16_f32 v92, v82, v83
	v_pk_mul_f32 v[82:83], v[88:89], v[100:101] op_sel_hi:[1,0]
	s_nop 0
	v_pk_mul_f32 v[86:87], v[82:83], s[20:21] op_sel_hi:[1,0]
	s_nop 0
	v_exp_f32_e32 v86, v86
	v_exp_f32_e32 v87, v87
	s_nop 0
	v_pk_add_f32 v[86:87], v[86:87], 1.0 op_sel_hi:[1,0]
	s_nop 0
	v_rcp_f32_e32 v86, v86
	v_rcp_f32_e32 v87, v87
	s_nop 0
	v_pk_mul_f32 v[82:83], v[82:83], v[86:87]
	s_nop 0
	v_pk_mul_f32 v[82:83], v[84:85], v[82:83]
	s_nop 0
	v_cvt_pk_bf16_f32 v93, v82, v83
	v_lshl_add_u64 v[82:83], v[98:99], 0, v[114:115]
	global_store_dwordx4 v[82:83], v[90:93], off
	ds_read_b32 v84, v148 offset:192
	v_or_b32_e32 v82, 48, v147
	v_mad_i64_i32 v[82:83], s[8:9], v82, s7, v[140:141]
	s_waitcnt lgkmcnt(0)
	v_pk_mul_f32 v[78:79], v[78:79], v[84:85] op_sel_hi:[1,0]
	s_nop 0
	v_pk_mul_f32 v[86:87], v[78:79], s[20:21] op_sel_hi:[1,0]
	v_pk_mul_f32 v[74:75], v[74:75], v[84:85] op_sel_hi:[1,0]
	v_exp_f32_e32 v86, v86
	v_exp_f32_e32 v87, v87
	v_pk_mul_f32 v[76:77], v[76:77], v[84:85] op_sel_hi:[1,0]
	v_pk_mul_f32 v[70:71], v[70:71], v[84:85] op_sel_hi:[1,0]
	v_pk_mul_f32 v[66:67], v[66:67], v[84:85] op_sel_hi:[1,0]
	v_pk_add_f32 v[86:87], v[86:87], 1.0 op_sel_hi:[1,0]
	v_pk_mul_f32 v[68:69], v[68:69], v[84:85] op_sel_hi:[1,0]
	v_rcp_f32_e32 v86, v86
	v_rcp_f32_e32 v87, v87
	s_nop 0
	v_pk_mul_f32 v[78:79], v[78:79], v[86:87]
	s_nop 0
	v_pk_mul_f32 v[74:75], v[74:75], v[78:79]
	v_pk_mul_f32 v[78:79], v[80:81], v[84:85] op_sel_hi:[1,0]
	v_cvt_pk_bf16_f32 v74, v74, v75
	s_nop 0
	v_pk_mul_f32 v[80:81], v[78:79], s[20:21] op_sel_hi:[1,0]
	s_nop 0
	v_exp_f32_e32 v80, v80
	v_exp_f32_e32 v81, v81
	s_nop 0
	v_pk_add_f32 v[80:81], v[80:81], 1.0 op_sel_hi:[1,0]
	s_nop 0
	v_rcp_f32_e32 v80, v80
	v_rcp_f32_e32 v81, v81
	s_nop 0
	v_pk_mul_f32 v[78:79], v[78:79], v[80:81]
	s_nop 0
	v_pk_mul_f32 v[76:77], v[76:77], v[78:79]
	s_nop 0
	v_cvt_pk_bf16_f32 v75, v76, v77
	v_pk_mul_f32 v[76:77], v[70:71], s[20:21] op_sel_hi:[1,0]
	s_nop 0
	v_exp_f32_e32 v76, v76
	v_exp_f32_e32 v77, v77
	s_nop 0
	v_pk_add_f32 v[76:77], v[76:77], 1.0 op_sel_hi:[1,0]
	s_nop 0
	v_rcp_f32_e32 v76, v76
	v_rcp_f32_e32 v77, v77
	s_nop 0
	v_pk_mul_f32 v[70:71], v[70:71], v[76:77]
	s_nop 0
	v_pk_mul_f32 v[66:67], v[66:67], v[70:71]
	s_nop 0
	v_cvt_pk_bf16_f32 v76, v66, v67
	v_pk_mul_f32 v[66:67], v[72:73], v[84:85] op_sel_hi:[1,0]
	s_nop 0
	v_pk_mul_f32 v[70:71], v[66:67], s[20:21] op_sel_hi:[1,0]
	s_nop 0
	v_exp_f32_e32 v70, v70
	v_exp_f32_e32 v71, v71
	s_nop 0
	v_pk_add_f32 v[70:71], v[70:71], 1.0 op_sel_hi:[1,0]
	s_nop 0
	v_rcp_f32_e32 v70, v70
	v_rcp_f32_e32 v71, v71
	s_nop 0
	v_pk_mul_f32 v[66:67], v[66:67], v[70:71]
	s_nop 0
	v_pk_mul_f32 v[66:67], v[68:69], v[66:67]
	s_nop 0
	v_cvt_pk_bf16_f32 v77, v66, v67
	v_lshl_add_u64 v[66:67], v[82:83], 0, v[114:115]
	global_store_dwordx4 v[66:67], v[74:77], off
	ds_read_b32 v68, v148 offset:512
	v_add_u32_e32 v66, 0x80, v147
	v_mad_i64_i32 v[66:67], s[8:9], v66, s7, v[140:141]
	s_waitcnt lgkmcnt(0)
	v_pk_mul_f32 v[62:63], v[62:63], v[68:69] op_sel_hi:[1,0]
	s_nop 0
	v_pk_mul_f32 v[70:71], v[62:63], s[20:21] op_sel_hi:[1,0]
	v_pk_mul_f32 v[58:59], v[58:59], v[68:69] op_sel_hi:[1,0]
	v_exp_f32_e32 v70, v70
	v_exp_f32_e32 v71, v71
	v_pk_mul_f32 v[60:61], v[60:61], v[68:69] op_sel_hi:[1,0]
	v_pk_mul_f32 v[54:55], v[54:55], v[68:69] op_sel_hi:[1,0]
	v_pk_mul_f32 v[50:51], v[50:51], v[68:69] op_sel_hi:[1,0]
	v_pk_add_f32 v[70:71], v[70:71], 1.0 op_sel_hi:[1,0]
	v_pk_mul_f32 v[52:53], v[52:53], v[68:69] op_sel_hi:[1,0]
	v_rcp_f32_e32 v70, v70
	v_rcp_f32_e32 v71, v71
	s_nop 0
	v_pk_mul_f32 v[62:63], v[62:63], v[70:71]
	s_nop 0
	v_pk_mul_f32 v[58:59], v[58:59], v[62:63]
	v_pk_mul_f32 v[62:63], v[64:65], v[68:69] op_sel_hi:[1,0]
	v_cvt_pk_bf16_f32 v58, v58, v59
	s_nop 0
	v_pk_mul_f32 v[64:65], v[62:63], s[20:21] op_sel_hi:[1,0]
	s_nop 0
	v_exp_f32_e32 v64, v64
	v_exp_f32_e32 v65, v65
	s_nop 0
	v_pk_add_f32 v[64:65], v[64:65], 1.0 op_sel_hi:[1,0]
	s_nop 0
	v_rcp_f32_e32 v64, v64
	v_rcp_f32_e32 v65, v65
	s_nop 0
	v_pk_mul_f32 v[62:63], v[62:63], v[64:65]
	s_nop 0
	v_pk_mul_f32 v[60:61], v[60:61], v[62:63]
	s_nop 0
	v_cvt_pk_bf16_f32 v59, v60, v61
	v_pk_mul_f32 v[60:61], v[54:55], s[20:21] op_sel_hi:[1,0]
	s_nop 0
	v_exp_f32_e32 v60, v60
	v_exp_f32_e32 v61, v61
	s_nop 0
	v_pk_add_f32 v[60:61], v[60:61], 1.0 op_sel_hi:[1,0]
	s_nop 0
	v_rcp_f32_e32 v60, v60
	v_rcp_f32_e32 v61, v61
	s_nop 0
	v_pk_mul_f32 v[54:55], v[54:55], v[60:61]
	s_nop 0
	v_pk_mul_f32 v[50:51], v[50:51], v[54:55]
	s_nop 0
	v_cvt_pk_bf16_f32 v60, v50, v51
	v_pk_mul_f32 v[50:51], v[56:57], v[68:69] op_sel_hi:[1,0]
	s_nop 0
	v_pk_mul_f32 v[54:55], v[50:51], s[20:21] op_sel_hi:[1,0]
	s_nop 0
	v_exp_f32_e32 v54, v54
	v_exp_f32_e32 v55, v55
	s_nop 0
	v_pk_add_f32 v[54:55], v[54:55], 1.0 op_sel_hi:[1,0]
	s_nop 0
	v_rcp_f32_e32 v54, v54
	v_rcp_f32_e32 v55, v55
	s_nop 0
	v_pk_mul_f32 v[50:51], v[50:51], v[54:55]
	s_nop 0
	v_pk_mul_f32 v[50:51], v[52:53], v[50:51]
	s_nop 0
	v_cvt_pk_bf16_f32 v61, v50, v51
	v_lshl_add_u64 v[50:51], v[66:67], 0, v[114:115]
	global_store_dwordx4 v[50:51], v[58:61], off
	ds_read_b32 v52, v148 offset:576
	v_add_u32_e32 v50, 0x90, v147
	v_mad_i64_i32 v[50:51], s[8:9], v50, s7, v[140:141]
	s_waitcnt lgkmcnt(0)
	v_pk_mul_f32 v[46:47], v[46:47], v[52:53] op_sel_hi:[1,0]
	s_nop 0
	v_pk_mul_f32 v[54:55], v[46:47], s[20:21] op_sel_hi:[1,0]
	v_pk_mul_f32 v[42:43], v[42:43], v[52:53] op_sel_hi:[1,0]
	v_exp_f32_e32 v54, v54
	v_exp_f32_e32 v55, v55
	v_pk_mul_f32 v[44:45], v[44:45], v[52:53] op_sel_hi:[1,0]
	v_pk_mul_f32 v[38:39], v[38:39], v[52:53] op_sel_hi:[1,0]
	v_pk_mul_f32 v[34:35], v[34:35], v[52:53] op_sel_hi:[1,0]
	v_pk_add_f32 v[54:55], v[54:55], 1.0 op_sel_hi:[1,0]
	v_pk_mul_f32 v[36:37], v[36:37], v[52:53] op_sel_hi:[1,0]
	v_rcp_f32_e32 v54, v54
	v_rcp_f32_e32 v55, v55
	s_nop 0
	v_pk_mul_f32 v[46:47], v[46:47], v[54:55]
	s_nop 0
	v_pk_mul_f32 v[42:43], v[42:43], v[46:47]
	v_pk_mul_f32 v[46:47], v[48:49], v[52:53] op_sel_hi:[1,0]
	v_cvt_pk_bf16_f32 v42, v42, v43
	s_nop 0
	v_pk_mul_f32 v[48:49], v[46:47], s[20:21] op_sel_hi:[1,0]
	s_nop 0
	v_exp_f32_e32 v48, v48
	v_exp_f32_e32 v49, v49
	s_nop 0
	v_pk_add_f32 v[48:49], v[48:49], 1.0 op_sel_hi:[1,0]
	s_nop 0
	v_rcp_f32_e32 v48, v48
	v_rcp_f32_e32 v49, v49
	s_nop 0
	v_pk_mul_f32 v[46:47], v[46:47], v[48:49]
	s_nop 0
	v_pk_mul_f32 v[44:45], v[44:45], v[46:47]
	s_nop 0
	v_cvt_pk_bf16_f32 v43, v44, v45
	v_pk_mul_f32 v[44:45], v[38:39], s[20:21] op_sel_hi:[1,0]
	s_nop 0
	v_exp_f32_e32 v44, v44
	v_exp_f32_e32 v45, v45
	s_nop 0
	v_pk_add_f32 v[44:45], v[44:45], 1.0 op_sel_hi:[1,0]
	s_nop 0
	v_rcp_f32_e32 v44, v44
	v_rcp_f32_e32 v45, v45
	s_nop 0
	v_pk_mul_f32 v[38:39], v[38:39], v[44:45]
	s_nop 0
	v_pk_mul_f32 v[34:35], v[34:35], v[38:39]
	s_nop 0
	v_cvt_pk_bf16_f32 v44, v34, v35
	v_pk_mul_f32 v[34:35], v[40:41], v[52:53] op_sel_hi:[1,0]
	s_nop 0
	v_pk_mul_f32 v[38:39], v[34:35], s[20:21] op_sel_hi:[1,0]
	s_nop 0
	v_exp_f32_e32 v38, v38
	v_exp_f32_e32 v39, v39
	s_nop 0
	v_pk_add_f32 v[38:39], v[38:39], 1.0 op_sel_hi:[1,0]
	s_nop 0
	v_rcp_f32_e32 v38, v38
	v_rcp_f32_e32 v39, v39
	s_nop 0
	v_pk_mul_f32 v[34:35], v[34:35], v[38:39]
	s_nop 0
	v_pk_mul_f32 v[34:35], v[36:37], v[34:35]
	s_nop 0
	v_cvt_pk_bf16_f32 v45, v34, v35
	v_lshl_add_u64 v[34:35], v[50:51], 0, v[114:115]
	global_store_dwordx4 v[34:35], v[42:45], off
	ds_read_b32 v36, v148 offset:640
	v_add_u32_e32 v34, 0xa0, v147
	v_mad_i64_i32 v[34:35], s[8:9], v34, s7, v[140:141]
	s_waitcnt lgkmcnt(0)
	v_pk_mul_f32 v[30:31], v[30:31], v[36:37] op_sel_hi:[1,0]
	s_nop 0
	v_pk_mul_f32 v[38:39], v[30:31], s[20:21] op_sel_hi:[1,0]
	v_pk_mul_f32 v[26:27], v[26:27], v[36:37] op_sel_hi:[1,0]
	v_exp_f32_e32 v38, v38
	v_exp_f32_e32 v39, v39
	v_pk_mul_f32 v[28:29], v[28:29], v[36:37] op_sel_hi:[1,0]
	v_pk_mul_f32 v[22:23], v[22:23], v[36:37] op_sel_hi:[1,0]
	v_pk_mul_f32 v[18:19], v[18:19], v[36:37] op_sel_hi:[1,0]
	v_pk_add_f32 v[38:39], v[38:39], 1.0 op_sel_hi:[1,0]
	v_pk_mul_f32 v[20:21], v[20:21], v[36:37] op_sel_hi:[1,0]
	v_rcp_f32_e32 v38, v38
	v_rcp_f32_e32 v39, v39
	s_nop 0
	v_pk_mul_f32 v[30:31], v[30:31], v[38:39]
	s_nop 0
	v_pk_mul_f32 v[26:27], v[26:27], v[30:31]
	v_pk_mul_f32 v[30:31], v[32:33], v[36:37] op_sel_hi:[1,0]
	v_cvt_pk_bf16_f32 v26, v26, v27
	s_nop 0
	v_pk_mul_f32 v[32:33], v[30:31], s[20:21] op_sel_hi:[1,0]
	s_nop 0
	v_exp_f32_e32 v32, v32
	v_exp_f32_e32 v33, v33
	s_nop 0
	v_pk_add_f32 v[32:33], v[32:33], 1.0 op_sel_hi:[1,0]
	s_nop 0
	v_rcp_f32_e32 v32, v32
	v_rcp_f32_e32 v33, v33
	s_nop 0
	v_pk_mul_f32 v[30:31], v[30:31], v[32:33]
	s_nop 0
	v_pk_mul_f32 v[28:29], v[28:29], v[30:31]
	s_nop 0
	v_cvt_pk_bf16_f32 v27, v28, v29
	v_pk_mul_f32 v[28:29], v[22:23], s[20:21] op_sel_hi:[1,0]
	s_nop 0
	v_exp_f32_e32 v28, v28
	v_exp_f32_e32 v29, v29
	s_nop 0
	v_pk_add_f32 v[28:29], v[28:29], 1.0 op_sel_hi:[1,0]
	s_nop 0
	v_rcp_f32_e32 v28, v28
	v_rcp_f32_e32 v29, v29
	s_nop 0
	v_pk_mul_f32 v[22:23], v[22:23], v[28:29]
	s_nop 0
	v_pk_mul_f32 v[18:19], v[18:19], v[22:23]
	s_nop 0
	v_cvt_pk_bf16_f32 v28, v18, v19
	v_pk_mul_f32 v[18:19], v[24:25], v[36:37] op_sel_hi:[1,0]
	s_nop 0
	v_pk_mul_f32 v[22:23], v[18:19], s[20:21] op_sel_hi:[1,0]
	s_nop 0
	v_exp_f32_e32 v22, v22
	v_exp_f32_e32 v23, v23
	s_nop 0
	v_pk_add_f32 v[22:23], v[22:23], 1.0 op_sel_hi:[1,0]
	s_nop 0
	v_rcp_f32_e32 v22, v22
	v_rcp_f32_e32 v23, v23
	s_nop 0
	v_pk_mul_f32 v[18:19], v[18:19], v[22:23]
	s_nop 0
	v_pk_mul_f32 v[18:19], v[20:21], v[18:19]
	s_nop 0
	v_cvt_pk_bf16_f32 v29, v18, v19
	v_lshl_add_u64 v[18:19], v[34:35], 0, v[114:115]
	global_store_dwordx4 v[18:19], v[26:29], off
	ds_read_b32 v20, v148 offset:704
	v_add_u32_e32 v18, 0xb0, v147
	v_mad_i64_i32 v[18:19], s[8:9], v18, s7, v[140:141]
	s_mov_b64 s[8:9], -1
	s_waitcnt lgkmcnt(0)
	v_pk_mul_f32 v[14:15], v[14:15], v[20:21] op_sel_hi:[1,0]
	v_pk_mul_f32 v[10:11], v[10:11], v[20:21] op_sel_hi:[1,0]
	v_pk_mul_f32 v[22:23], v[14:15], s[20:21] op_sel_hi:[1,0]
	v_pk_mul_f32 v[12:13], v[12:13], v[20:21] op_sel_hi:[1,0]
	v_exp_f32_e32 v22, v22
	v_exp_f32_e32 v23, v23
	v_pk_mul_f32 v[6:7], v[6:7], v[20:21] op_sel_hi:[1,0]
	v_pk_mul_f32 v[2:3], v[2:3], v[20:21] op_sel_hi:[1,0]
	v_pk_mul_f32 v[4:5], v[4:5], v[20:21] op_sel_hi:[1,0]
	v_pk_add_f32 v[22:23], v[22:23], 1.0 op_sel_hi:[1,0]
	s_nop 0
	v_rcp_f32_e32 v22, v22
	v_rcp_f32_e32 v23, v23
	s_nop 0
	v_pk_mul_f32 v[14:15], v[14:15], v[22:23]
	s_nop 0
	v_pk_mul_f32 v[10:11], v[10:11], v[14:15]
	v_pk_mul_f32 v[14:15], v[16:17], v[20:21] op_sel_hi:[1,0]
	v_cvt_pk_bf16_f32 v10, v10, v11
	s_nop 0
	v_pk_mul_f32 v[16:17], v[14:15], s[20:21] op_sel_hi:[1,0]
	s_nop 0
	v_exp_f32_e32 v16, v16
	v_exp_f32_e32 v17, v17
	s_nop 0
	v_pk_add_f32 v[16:17], v[16:17], 1.0 op_sel_hi:[1,0]
	s_nop 0
	v_rcp_f32_e32 v16, v16
	v_rcp_f32_e32 v17, v17
	s_nop 0
	v_pk_mul_f32 v[14:15], v[14:15], v[16:17]
	s_nop 0
	v_pk_mul_f32 v[12:13], v[12:13], v[14:15]
	s_nop 0
	v_cvt_pk_bf16_f32 v11, v12, v13
	v_pk_mul_f32 v[12:13], v[6:7], s[20:21] op_sel_hi:[1,0]
	s_nop 0
	v_exp_f32_e32 v12, v12
	v_exp_f32_e32 v13, v13
	s_nop 0
	v_pk_add_f32 v[12:13], v[12:13], 1.0 op_sel_hi:[1,0]
	s_nop 0
	v_rcp_f32_e32 v12, v12
	v_rcp_f32_e32 v13, v13
	s_nop 0
	v_pk_mul_f32 v[6:7], v[6:7], v[12:13]
	s_nop 0
	v_pk_mul_f32 v[2:3], v[2:3], v[6:7]
	s_nop 0
	v_cvt_pk_bf16_f32 v12, v2, v3
	v_pk_mul_f32 v[2:3], v[8:9], v[20:21] op_sel_hi:[1,0]
	s_nop 0
	v_pk_mul_f32 v[6:7], v[2:3], s[20:21] op_sel_hi:[1,0]
	s_nop 0
	v_exp_f32_e32 v6, v6
	v_exp_f32_e32 v7, v7
	s_nop 0
	v_pk_add_f32 v[6:7], v[6:7], 1.0 op_sel_hi:[1,0]
	s_nop 0
	v_rcp_f32_e32 v6, v6
	v_rcp_f32_e32 v7, v7
	s_nop 0
	v_pk_mul_f32 v[2:3], v[2:3], v[6:7]
	s_nop 0
	v_pk_mul_f32 v[2:3], v[4:5], v[2:3]
	s_nop 0
	v_cvt_pk_bf16_f32 v13, v2, v3
	v_lshl_add_u64 v[2:3], v[18:19], 0, v[114:115]
	global_store_dwordx4 v[2:3], v[10:13], off
	s_mov_b32 s100, 1
	s_cbranch_vccnz .LBB0_956
	s_andn2_b64 vcc, exec, s[0:1]
	s_cbranch_vccnz .LBB0_955
	s_barrier
	s_branch .LBB0_955
.LBB0_966:
	s_mov_b32 s100, 0
	s_waitcnt vmcnt(0)
	s_movk_i32 s57, 0x300
	s_mov_b32 s64, s75
	v_readlane_b32 s16, v254, 26
	s_barrier

	.amdhsa_kernel _Z4mega4Args
		.amdhsa_group_segment_fixed_size 0
		.amdhsa_private_segment_fixed_size 0
		.amdhsa_kernarg_size 472
		.amdhsa_user_sgpr_count 2
		.amdhsa_user_sgpr_dispatch_ptr 0
		.amdhsa_user_sgpr_queue_ptr 0
		.amdhsa_user_sgpr_kernarg_segment_ptr 1
		.amdhsa_user_sgpr_dispatch_id 0
		.amdhsa_user_sgpr_kernarg_preload_length 0
		.amdhsa_user_sgpr_kernarg_preload_offset 0
		.amdhsa_user_sgpr_private_segment_size 0
		.amdhsa_uses_dynamic_stack 0
		.amdhsa_enable_private_segment 0
		.amdhsa_system_sgpr_workgroup_id_x 1
		.amdhsa_system_sgpr_workgroup_id_y 0
		.amdhsa_system_sgpr_workgroup_id_z 0
		.amdhsa_system_sgpr_workgroup_info 0
		.amdhsa_system_vgpr_workitem_id 2
		.amdhsa_next_free_vgpr 256
		.amdhsa_next_free_sgpr 102
		.amdhsa_accum_offset 256
		.amdhsa_reserve_vcc 1
		.amdhsa_float_round_mode_32 0
		.amdhsa_float_round_mode_16_64 0
		.amdhsa_float_denorm_mode_32 3
		.amdhsa_float_denorm_mode_16_64 3
		.amdhsa_dx10_clamp 1
		.amdhsa_ieee_mode 1
		.amdhsa_fp16_overflow 0
		.amdhsa_tg_split 0
		.amdhsa_exception_fp_ieee_invalid_op 0
		.amdhsa_exception_fp_denorm_src 0
		.amdhsa_exception_fp_ieee_div_zero 0
		.amdhsa_exception_fp_ieee_overflow 0
		.amdhsa_exception_fp_ieee_underflow 0
		.amdhsa_exception_fp_ieee_inexact 0
		.amdhsa_exception_int_div_zero 0
	.end_amdhsa_kernel

amdhsa.kernels:
  - .agpr_count:     0
    .args:
      - .offset:         0
        .size:           216
        .value_kind:     by_value
      - .offset:         216
        .size:           4
        .value_kind:     hidden_block_count_x
      - .offset:         220
        .size:           4
        .value_kind:     hidden_block_count_y
      - .offset:         224
        .size:           4
        .value_kind:     hidden_block_count_z
      - .offset:         228
        .size:           2
        .value_kind:     hidden_group_size_x
      - .offset:         230
        .size:           2
        .value_kind:     hidden_group_size_y
      - .offset:         232
        .size:           2
        .value_kind:     hidden_group_size_z
      - .offset:         234
        .size:           2
        .value_kind:     hidden_remainder_x
      - .offset:         236
        .size:           2
        .value_kind:     hidden_remainder_y
      - .offset:         238
        .size:           2
        .value_kind:     hidden_remainder_z
      - .offset:         256
        .size:           8
        .value_kind:     hidden_global_offset_x
      - .offset:         264
        .size:           8
        .value_kind:     hidden_global_offset_y
      - .offset:         272
        .size:           8
        .value_kind:     hidden_global_offset_z
      - .offset:         280
        .size:           2
        .value_kind:     hidden_grid_dims
      - .offset:         304
        .size:           8
        .value_kind:     hidden_multigrid_sync_arg
      - .offset:         336
        .size:           4
        .value_kind:     hidden_dynamic_lds_size
    .group_segment_fixed_size: 0
    .kernarg_segment_align: 8
    .kernarg_segment_size: 472
    .language:       OpenCL C
    .language_version:
      - 2
      - 0
    .max_flat_workgroup_size: 512
    .name:           _Z4mega4Args
    .private_segment_fixed_size: 0
    .sgpr_count:     108
    .sgpr_spill_count: 272
    .symbol:         _Z4mega4Args.kd
    .uniform_work_group_size: 1
    .uses_dynamic_stack: false
    .vgpr_count:     256
    .vgpr_spill_count: 0
    .wavefront_size: 64
